# phase 7 main-tile epilogue rewritten by hand: x1 rows two blocks ahead in flight, accumulators exchanged between 8-lane halves (DPP row_ror:8 + select) so each 16-byte access covers 8 rows x 128 B
# speedup vs baseline: 1.0577x; 1.0108x over previous
; #define PG8_STAGE(bufoff, gbase, voff) do { _Pragma("unroll") for (int _i = 0; _i < 2; ++_i) \
;         __builtin_amdgcn_global_load_lds((const unsigned*)((const char*)(gbase) + (voff)[_i]), (PG8_LAS unsigned*)(lds + (bufoff) + ldsw + _i * 8192), 16, 0, 0); } while (0)
; #define PG8_LDA(dst, b, h) do { _Pragma("unroll") for (int m = 0; m < 4; ++m) _Pragma("unroll") for (int k = 0; k < 2; ++k) dst[m][k] = *(const PG8_LAS bf16x8*)(lds + PG8_SA(b, h) + aoff + m * 2048 + k * 1024); } while (0)
; #define PG8_LDB(dst, b, h) do { _Pragma("unroll") for (int n = 0; n < 2; ++n) _Pragma("unroll") for (int k = 0; k < 2; ++k) dst[n][k] = *(const PG8_LAS bf16x8*)(lds + PG8_SB(b, h) + boff + n * 2048 + k * 1024); } while (0)
; #define PG8_MMA(ai, bj, At, Bt) do { __builtin_amdgcn_s_setprio(1); _Pragma("unroll") for (int m = 0; m < 4; ++m) _Pragma("unroll") for (int n = 0; n < 2; ++n) _Pragma("unroll") for (int k = 0; k < 2; ++k) \
;         acc[ai][bj][m][n] = __builtin_amdgcn_mfma_f32_16x16x32_bf16(Bt[n][k], At[m][k], acc[ai][bj][m][n], 0, 0, 0); __builtin_amdgcn_s_setprio(0); } while (0)
; #define PG8_WAIT_L(n) asm volatile("s_waitcnt lgkmcnt(" #n ")" ::: "memory")
; #define PG8_BAR __builtin_amdgcn_s_barrier()
; #define PG8_SCHED __builtin_amdgcn_sched_barrier(0)
; template <class Epi, class Sched>
; __device__ __forceinline__ void gemm_phase(PG8_LAS unsigned char* lds, const Gemm g, const Sched& S, const Epi& E) {
;     ...
;             PG8_LDB(B0, 0, 0); PG8_SCHED; PG8_LDA(At, 0, 0); PG8_STAGE(PG8_SA(1, 1), a1 + hstep, voffA);
;             PG8_WAIT_L(8); PG8_BAR; PG8_WAIT_L(0); PG8_MMA(0, 0, At, B0); PG8_BAR; PG8_SCHED;
;             PG8_LDB(B1, 0, 1); PG8_STAGE(PG8_SB(0, 0), b2, voffB);
;             PG8_BAR; PG8_WAIT_L(0); PG8_MMA(0, 1, At, B1); PG8_BAR;
;             PG8_LDA(At, 0, 1); PG8_STAGE(PG8_SA(0, 0), a2, voffA);
;             PG8_BAR; PG8_WAIT_L(0); PG8_MMA(1, 0, At, B0); PG8_BAR; PG8_SCHED;
;             PG8_STAGE(PG8_SB(0, 1), b2 + hstep, voffB);
.LBB0_828:
	ds_read_b128 v[138:141], v147
	ds_read_b128 v[164:167], v148
	ds_read_b128 v[168:171], v149
	ds_read_b128 v[172:175], v150
	s_add_u32 s24, s22, 0xfff00080
	s_addc_u32 s25, s23, -1
	s_cmp_eq_u32 s54, 60
	s_cselect_b32 s27, s11, s25
	s_cselect_b32 s26, s50, s24
	s_cselect_b32 s25, s9, s53
	s_cselect_b32 s24, s51, s52
	s_mov_b32 m0, s48
	v_lshl_add_u64 v[208:209], s[22:23], 0, v[134:135]
	ds_read_b128 v[176:179], v145
	ds_read_b128 v[180:183], v145 offset:1024
	ds_read_b128 v[184:187], v145 offset:2048
	ds_read_b128 v[188:191], v145 offset:3072
	ds_read_b128 v[192:195], v145 offset:4096
	ds_read_b128 v[196:199], v145 offset:5120
	ds_read_b128 v[200:203], v145 offset:6144
	ds_read_b128 v[204:207], v145 offset:7168
	global_load_lds_dwordx4 v[208:209], off
	v_lshl_add_u64 v[208:209], s[22:23], 0, v[136:137]
	s_mov_b32 m0, s49
	s_nop 0
	global_load_lds_dwordx4 v[208:209], off
	s_waitcnt lgkmcnt(8)
	s_barrier
	s_waitcnt lgkmcnt(0)
	s_setprio 1
	s_waitcnt lgkmcnt(0)
	v_mfma_f32_16x16x32_bf16 v[126:129], v[138:141], v[176:179], v[126:129]
	v_mfma_f32_16x16x32_bf16 v[122:125], v[168:171], v[176:179], v[122:125]
	v_mfma_f32_16x16x32_bf16 v[114:117], v[138:141], v[184:187], v[114:117]
	v_mfma_f32_16x16x32_bf16 v[106:109], v[168:171], v[184:187], v[106:109]
	v_mfma_f32_16x16x32_bf16 v[94:97], v[138:141], v[192:195], v[94:97]
	v_mfma_f32_16x16x32_bf16 v[90:93], v[168:171], v[192:195], v[90:93]
	v_mfma_f32_16x16x32_bf16 v[78:81], v[138:141], v[200:203], v[78:81]
	v_mfma_f32_16x16x32_bf16 v[74:77], v[168:171], v[200:203], v[74:77]
	v_mfma_f32_16x16x32_bf16 v[126:129], v[164:167], v[180:183], v[126:129]
	v_mfma_f32_16x16x32_bf16 v[122:125], v[172:175], v[180:183], v[122:125]
	v_mfma_f32_16x16x32_bf16 v[114:117], v[164:167], v[188:191], v[114:117]
	v_mfma_f32_16x16x32_bf16 v[106:109], v[172:175], v[188:191], v[106:109]
	v_mfma_f32_16x16x32_bf16 v[94:97], v[164:167], v[196:199], v[94:97]
	v_mfma_f32_16x16x32_bf16 v[90:93], v[172:175], v[196:199], v[90:93]
	v_mfma_f32_16x16x32_bf16 v[78:81], v[164:167], v[204:207], v[78:81]
	v_mfma_f32_16x16x32_bf16 v[74:77], v[172:175], v[204:207], v[74:77]
	s_setprio 0
	s_barrier
	s_mov_b32 m0, s19
	v_lshl_add_u64 v[224:225], s[24:25], 0, v[132:133]
	ds_read_b128 v[208:211], v151
	ds_read_b128 v[212:215], v152
	ds_read_b128 v[216:219], v153
	ds_read_b128 v[220:223], v154
	global_load_lds_dwordx4 v[224:225], off
	v_lshl_add_u64 v[226:227], s[24:25], 0, v[130:131]
	s_mov_b32 m0, s21
	s_nop 0
	global_load_lds_dwordx4 v[226:227], off
	s_barrier
	s_waitcnt lgkmcnt(0)
	s_setprio 1
	s_waitcnt lgkmcnt(0)
	v_mfma_f32_16x16x32_bf16 v[118:121], v[208:211], v[176:179], v[118:121]
	v_mfma_f32_16x16x32_bf16 v[110:113], v[216:219], v[176:179], v[110:113]
	v_mfma_f32_16x16x32_bf16 v[102:105], v[208:211], v[184:187], v[102:105]
	v_mfma_f32_16x16x32_bf16 v[98:101], v[216:219], v[184:187], v[98:101]
	v_mfma_f32_16x16x32_bf16 v[86:89], v[208:211], v[192:195], v[86:89]
	v_mfma_f32_16x16x32_bf16 v[82:85], v[216:219], v[192:195], v[82:85]
	v_mfma_f32_16x16x32_bf16 v[70:73], v[208:211], v[200:203], v[70:73]
	v_mfma_f32_16x16x32_bf16 v[66:69], v[216:219], v[200:203], v[66:69]
	v_mfma_f32_16x16x32_bf16 v[118:121], v[212:215], v[180:183], v[118:121]
	v_mfma_f32_16x16x32_bf16 v[110:113], v[220:223], v[180:183], v[110:113]
	v_mfma_f32_16x16x32_bf16 v[102:105], v[212:215], v[188:191], v[102:105]
	v_mfma_f32_16x16x32_bf16 v[98:101], v[220:223], v[188:191], v[98:101]
	v_mfma_f32_16x16x32_bf16 v[86:89], v[212:215], v[196:199], v[86:89]
	v_mfma_f32_16x16x32_bf16 v[82:85], v[220:223], v[196:199], v[82:85]
	v_mfma_f32_16x16x32_bf16 v[70:73], v[212:215], v[204:207], v[70:73]
	v_mfma_f32_16x16x32_bf16 v[66:69], v[220:223], v[204:207], v[66:69]
	s_setprio 0
	s_mov_b32 m0, s35
	v_lshl_add_u64 v[228:229], s[26:27], 0, v[132:133]
	s_barrier
	ds_read_b128 v[176:179], v145 offset:16384
	ds_read_b128 v[180:183], v145 offset:17408
	ds_read_b128 v[184:187], v145 offset:18432
	ds_read_b128 v[188:191], v145 offset:19456
	ds_read_b128 v[192:195], v145 offset:20480
	ds_read_b128 v[196:199], v145 offset:21504
	ds_read_b128 v[200:203], v145 offset:22528
	ds_read_b128 v[204:207], v145 offset:23552
	global_load_lds_dwordx4 v[228:229], off
	v_lshl_add_u64 v[230:231], s[26:27], 0, v[130:131]
	s_mov_b32 m0, s36
	s_nop 0
	global_load_lds_dwordx4 v[230:231], off
	s_barrier
	s_waitcnt lgkmcnt(0)
	s_setprio 1
	s_waitcnt lgkmcnt(0)
	v_mfma_f32_16x16x32_bf16 v[62:65], v[138:141], v[176:179], v[62:65]
	v_mfma_f32_16x16x32_bf16 v[58:61], v[168:171], v[176:179], v[58:61]
	v_mfma_f32_16x16x32_bf16 v[46:49], v[138:141], v[184:187], v[46:49]
	v_mfma_f32_16x16x32_bf16 v[42:45], v[168:171], v[184:187], v[42:45]
	v_mfma_f32_16x16x32_bf16 v[30:33], v[138:141], v[192:195], v[30:33]
	v_mfma_f32_16x16x32_bf16 v[26:29], v[168:171], v[192:195], v[26:29]
	v_mfma_f32_16x16x32_bf16 v[14:17], v[138:141], v[200:203], v[14:17]
	v_mfma_f32_16x16x32_bf16 v[10:13], v[168:171], v[200:203], v[10:13]
	v_mfma_f32_16x16x32_bf16 v[62:65], v[164:167], v[180:183], v[62:65]
	v_mfma_f32_16x16x32_bf16 v[58:61], v[172:175], v[180:183], v[58:61]
	v_mfma_f32_16x16x32_bf16 v[46:49], v[164:167], v[188:191], v[46:49]
	v_mfma_f32_16x16x32_bf16 v[42:45], v[172:175], v[188:191], v[42:45]
	v_mfma_f32_16x16x32_bf16 v[30:33], v[164:167], v[196:199], v[30:33]
	v_mfma_f32_16x16x32_bf16 v[26:29], v[172:175], v[196:199], v[26:29]
	v_mfma_f32_16x16x32_bf16 v[14:17], v[164:167], v[204:207], v[14:17]
	v_mfma_f32_16x16x32_bf16 v[10:13], v[172:175], v[204:207], v[10:13]
	s_setprio 0
	s_barrier
; #define PG8_STAGE(bufoff, gbase, voff) do { _Pragma("unroll") for (int _i = 0; _i < 2; ++_i) \
;         __builtin_amdgcn_global_load_lds((const unsigned*)((const char*)(gbase) + (voff)[_i]), (PG8_LAS unsigned*)(lds + (bufoff) + ldsw + _i * 8192), 16, 0, 0); } while (0)
; #define PG8_LDA(dst, b, h) do { _Pragma("unroll") for (int m = 0; m < 4; ++m) _Pragma("unroll") for (int k = 0; k < 2; ++k) dst[m][k] = *(const PG8_LAS bf16x8*)(lds + PG8_SA(b, h) + aoff + m * 2048 + k * 1024); } while (0)
; #define PG8_LDB(dst, b, h) do { _Pragma("unroll") for (int n = 0; n < 2; ++n) _Pragma("unroll") for (int k = 0; k < 2; ++k) dst[n][k] = *(const PG8_LAS bf16x8*)(lds + PG8_SB(b, h) + boff + n * 2048 + k * 1024); } while (0)
; #define PG8_MMA(ai, bj, At, Bt) do { __builtin_amdgcn_s_setprio(1); _Pragma("unroll") for (int m = 0; m < 4; ++m) _Pragma("unroll") for (int n = 0; n < 2; ++n) _Pragma("unroll") for (int k = 0; k < 2; ++k) \
;         acc[ai][bj][m][n] = __builtin_amdgcn_mfma_f32_16x16x32_bf16(Bt[n][k], At[m][k], acc[ai][bj][m][n], 0, 0, 0); __builtin_amdgcn_s_setprio(0); } while (0)
; #define PG8_WAIT_V(n) asm volatile("s_waitcnt vmcnt(" #n ")" ::: "memory")
; #define PG8_WAIT_L(n) asm volatile("s_waitcnt lgkmcnt(" #n ")" ::: "memory")
; #define PG8_BAR __builtin_amdgcn_s_barrier()
; #define PG8_SCHED __builtin_amdgcn_sched_barrier(0)
; template <class Epi, class Sched>
; __device__ __forceinline__ void gemm_phase(PG8_LAS unsigned char* lds, const Gemm g, const Sched& S, const Epi& E) {
;     ...
;             PG8_STAGE(PG8_SB(0, 1), b2 + hstep, voffB);
;             PG8_WAIT_V(6); PG8_BAR; PG8_MMA(1, 1, At, B1); PG8_BAR;
;             PG8_LDB(B0, 1, 0); PG8_SCHED; PG8_LDA(At, 1, 0); PG8_STAGE(PG8_SA(0, 1), a2 + hstep, voffA);
;             PG8_WAIT_L(8); PG8_BAR; PG8_WAIT_L(0); PG8_MMA(0, 0, At, B0); PG8_BAR; PG8_SCHED;
;             PG8_LDB(B1, 1, 1); PG8_STAGE(PG8_SB(1, 0), b3, voffB);
;             PG8_BAR; PG8_WAIT_L(0); PG8_MMA(0, 1, At, B1); PG8_BAR;
;             PG8_LDA(At, 1, 1); PG8_STAGE(PG8_SA(1, 0), a3, voffA);
;             PG8_BAR; PG8_WAIT_L(0); PG8_MMA(1, 0, At, B0); PG8_BAR; PG8_SCHED;
	s_add_u32 s56, s24, 0x100000
	s_addc_u32 s57, s25, 0
	s_mov_b32 m0, s37
	v_lshl_add_u64 v[138:139], s[56:57], 0, v[132:133]
	global_load_lds_dwordx4 v[138:139], off
	v_lshl_add_u64 v[138:139], s[56:57], 0, v[130:131]
	s_mov_b32 m0, s38
	s_nop 0
	global_load_lds_dwordx4 v[138:139], off
	s_waitcnt vmcnt(6)
	s_barrier
	s_setprio 1
	v_mfma_f32_16x16x32_bf16 v[54:57], v[208:211], v[176:179], v[54:57]
	v_mfma_f32_16x16x32_bf16 v[50:53], v[216:219], v[176:179], v[50:53]
	v_mfma_f32_16x16x32_bf16 v[38:41], v[208:211], v[184:187], v[38:41]
	v_mfma_f32_16x16x32_bf16 v[34:37], v[216:219], v[184:187], v[34:37]
	v_mfma_f32_16x16x32_bf16 v[22:25], v[208:211], v[192:195], v[22:25]
	v_mfma_f32_16x16x32_bf16 v[18:21], v[216:219], v[192:195], v[18:21]
	v_mfma_f32_16x16x32_bf16 v[6:9], v[208:211], v[200:203], v[6:9]
	v_mfma_f32_16x16x32_bf16 v[2:5], v[216:219], v[200:203], v[2:5]
	v_mfma_f32_16x16x32_bf16 v[54:57], v[212:215], v[180:183], v[54:57]
	v_mfma_f32_16x16x32_bf16 v[50:53], v[220:223], v[180:183], v[50:53]
	v_mfma_f32_16x16x32_bf16 v[38:41], v[212:215], v[188:191], v[38:41]
	v_mfma_f32_16x16x32_bf16 v[34:37], v[220:223], v[188:191], v[34:37]
	v_mfma_f32_16x16x32_bf16 v[22:25], v[212:215], v[196:199], v[22:25]
	v_mfma_f32_16x16x32_bf16 v[18:21], v[220:223], v[196:199], v[18:21]
	v_mfma_f32_16x16x32_bf16 v[6:9], v[212:215], v[204:207], v[6:9]
	v_mfma_f32_16x16x32_bf16 v[2:5], v[220:223], v[204:207], v[2:5]
	s_setprio 0
	s_barrier
	ds_read_b128 v[138:141], v155
	ds_read_b128 v[164:167], v156
	ds_read_b128 v[168:171], v157
	ds_read_b128 v[172:175], v158
	s_add_u32 s26, s26, 0x100000
	s_addc_u32 s27, s27, 0
	s_mov_b32 m0, s39
	v_lshl_add_u64 v[208:209], s[26:27], 0, v[132:133]
	ds_read_b128 v[176:179], v145 offset:32768
	ds_read_b128 v[180:183], v145 offset:33792
	ds_read_b128 v[184:187], v145 offset:34816
	ds_read_b128 v[188:191], v145 offset:35840
	ds_read_b128 v[192:195], v145 offset:36864
	ds_read_b128 v[196:199], v145 offset:37888
	ds_read_b128 v[200:203], v145 offset:38912
	ds_read_b128 v[204:207], v145 offset:39936
	global_load_lds_dwordx4 v[208:209], off
	v_lshl_add_u64 v[208:209], s[26:27], 0, v[130:131]
	s_mov_b32 m0, s40
	s_nop 0
	global_load_lds_dwordx4 v[208:209], off
	s_waitcnt lgkmcnt(8)
	s_barrier
	s_waitcnt lgkmcnt(0)
	s_setprio 1
	s_waitcnt lgkmcnt(0)
	v_mfma_f32_16x16x32_bf16 v[126:129], v[138:141], v[176:179], v[126:129]
	v_mfma_f32_16x16x32_bf16 v[122:125], v[168:171], v[176:179], v[122:125]
	v_mfma_f32_16x16x32_bf16 v[114:117], v[138:141], v[184:187], v[114:117]
	v_mfma_f32_16x16x32_bf16 v[106:109], v[168:171], v[184:187], v[106:109]
	v_mfma_f32_16x16x32_bf16 v[94:97], v[138:141], v[192:195], v[94:97]
	v_mfma_f32_16x16x32_bf16 v[90:93], v[168:171], v[192:195], v[90:93]
	v_mfma_f32_16x16x32_bf16 v[78:81], v[138:141], v[200:203], v[78:81]
	v_mfma_f32_16x16x32_bf16 v[74:77], v[168:171], v[200:203], v[74:77]
	v_mfma_f32_16x16x32_bf16 v[126:129], v[164:167], v[180:183], v[126:129]
	v_mfma_f32_16x16x32_bf16 v[122:125], v[172:175], v[180:183], v[122:125]
	v_mfma_f32_16x16x32_bf16 v[114:117], v[164:167], v[188:191], v[114:117]
	v_mfma_f32_16x16x32_bf16 v[106:109], v[172:175], v[188:191], v[106:109]
	v_mfma_f32_16x16x32_bf16 v[94:97], v[164:167], v[196:199], v[94:97]
	v_mfma_f32_16x16x32_bf16 v[90:93], v[172:175], v[196:199], v[90:93]
	v_mfma_f32_16x16x32_bf16 v[78:81], v[164:167], v[204:207], v[78:81]
	v_mfma_f32_16x16x32_bf16 v[74:77], v[172:175], v[204:207], v[74:77]
	s_setprio 0
	s_barrier
	s_mov_b32 m0, s41
	v_lshl_add_u64 v[224:225], v[224:225], 0, s[6:7]
	ds_read_b128 v[208:211], v159
	ds_read_b128 v[212:215], v160
	ds_read_b128 v[216:219], v161
	ds_read_b128 v[220:223], v162
	global_load_lds_dwordx4 v[224:225], off
	v_lshl_add_u64 v[224:225], v[226:227], 0, s[6:7]
	s_mov_b32 m0, s42
	s_nop 0
	global_load_lds_dwordx4 v[224:225], off
	s_barrier
	s_waitcnt lgkmcnt(0)
	s_setprio 1
	s_waitcnt lgkmcnt(0)
	v_mfma_f32_16x16x32_bf16 v[118:121], v[208:211], v[176:179], v[118:121]
	v_mfma_f32_16x16x32_bf16 v[110:113], v[216:219], v[176:179], v[110:113]
	v_mfma_f32_16x16x32_bf16 v[102:105], v[208:211], v[184:187], v[102:105]
	v_mfma_f32_16x16x32_bf16 v[98:101], v[216:219], v[184:187], v[98:101]
	v_mfma_f32_16x16x32_bf16 v[86:89], v[208:211], v[192:195], v[86:89]
	v_mfma_f32_16x16x32_bf16 v[82:85], v[216:219], v[192:195], v[82:85]
	v_mfma_f32_16x16x32_bf16 v[70:73], v[208:211], v[200:203], v[70:73]
	v_mfma_f32_16x16x32_bf16 v[66:69], v[216:219], v[200:203], v[66:69]
	v_mfma_f32_16x16x32_bf16 v[118:121], v[212:215], v[180:183], v[118:121]
	v_mfma_f32_16x16x32_bf16 v[110:113], v[220:223], v[180:183], v[110:113]
	v_mfma_f32_16x16x32_bf16 v[102:105], v[212:215], v[188:191], v[102:105]
	v_mfma_f32_16x16x32_bf16 v[98:101], v[220:223], v[188:191], v[98:101]
	v_mfma_f32_16x16x32_bf16 v[86:89], v[212:215], v[196:199], v[86:89]
	v_mfma_f32_16x16x32_bf16 v[82:85], v[220:223], v[196:199], v[82:85]
	v_mfma_f32_16x16x32_bf16 v[70:73], v[212:215], v[204:207], v[70:73]
	v_mfma_f32_16x16x32_bf16 v[66:69], v[220:223], v[204:207], v[66:69]
	s_setprio 0
	s_mov_b32 m0, s43
	v_lshl_add_u64 v[224:225], v[228:229], 0, s[6:7]
	s_barrier
	ds_read_b128 v[176:179], v145 offset:49152
	ds_read_b128 v[180:183], v145 offset:50176
	ds_read_b128 v[184:187], v145 offset:51200
	ds_read_b128 v[188:191], v145 offset:52224
	ds_read_b128 v[192:195], v145 offset:53248
	ds_read_b128 v[196:199], v145 offset:54272
	ds_read_b128 v[200:203], v145 offset:55296
	ds_read_b128 v[204:207], v145 offset:56320
	global_load_lds_dwordx4 v[224:225], off
	v_lshl_add_u64 v[224:225], v[230:231], 0, s[6:7]
	s_mov_b32 m0, s44
	s_nop 0
	global_load_lds_dwordx4 v[224:225], off
	s_barrier
; #define PG8_STAGE(bufoff, gbase, voff) do { _Pragma("unroll") for (int _i = 0; _i < 2; ++_i) \
;         __builtin_amdgcn_global_load_lds((const unsigned*)((const char*)(gbase) + (voff)[_i]), (PG8_LAS unsigned*)(lds + (bufoff) + ldsw + _i * 8192), 16, 0, 0); } while (0)
; #define PG8_MMA(ai, bj, At, Bt) do { __builtin_amdgcn_s_setprio(1); _Pragma("unroll") for (int m = 0; m < 4; ++m) _Pragma("unroll") for (int n = 0; n < 2; ++n) _Pragma("unroll") for (int k = 0; k < 2; ++k) \
;         acc[ai][bj][m][n] = __builtin_amdgcn_mfma_f32_16x16x32_bf16(Bt[n][k], At[m][k], acc[ai][bj][m][n], 0, 0, 0); __builtin_amdgcn_s_setprio(0); } while (0)
; #define PG8_WAIT_V(n) asm volatile("s_waitcnt vmcnt(" #n ")" ::: "memory")
; #define PG8_WAIT_L(n) asm volatile("s_waitcnt lgkmcnt(" #n ")" ::: "memory")
; #define PG8_BAR __builtin_amdgcn_s_barrier()
; #define PG8_SCHED __builtin_amdgcn_sched_barrier(0)
; template <class Epi, class Sched>
; __device__ __forceinline__ void gemm_phase(PG8_LAS unsigned char* lds, const Gemm g, const Sched& S, const Epi& E) {
;     ...
;             PG8_BAR; PG8_WAIT_L(0); PG8_MMA(1, 0, At, B0); PG8_BAR; PG8_SCHED;
;             PG8_STAGE(PG8_SB(1, 1), b3 + hstep, voffB);
;             PG8_WAIT_V(6); PG8_BAR; PG8_MMA(1, 1, At, B1); PG8_BAR;
;   __device__ __forceinline__ void operator()(const acc8_t& acc, const pg8::Unit& u, int wr, int wc, int fr, int fq) const {
;     ...
;     for (int ai = 0; ai < 2; ai++)
; #pragma unroll
;       for (int m = 0; m < 4; m++) {
;         const size_t token = EPI_TOKEN(u, ai, m);
; #pragma unroll
;         for (int bj = 0; bj < 2; bj++)
; #pragma unroll
;           for (int n = 0; n < 2; n++) {
;             float* yp = out + O_Y + token * 1024 + EPI_COL(u, bj, n);
;             float4 y = *(const float4*)yp;
;             y.x += acc[ai][bj][m][n][0]; y.y += acc[ai][bj][m][n][1]; y.z += acc[ai][bj][m][n][2]; y.w += acc[ai][bj][m][n][3];
;             *(float4*)yp = y;
	s_waitcnt lgkmcnt(0)
	s_setprio 1
	s_waitcnt lgkmcnt(0)
	v_mfma_f32_16x16x32_bf16 v[62:65], v[138:141], v[176:179], v[62:65]
	v_mfma_f32_16x16x32_bf16 v[58:61], v[168:171], v[176:179], v[58:61]
	v_mfma_f32_16x16x32_bf16 v[46:49], v[138:141], v[184:187], v[46:49]
	v_mfma_f32_16x16x32_bf16 v[42:45], v[168:171], v[184:187], v[42:45]
	v_mfma_f32_16x16x32_bf16 v[30:33], v[138:141], v[192:195], v[30:33]
	v_mfma_f32_16x16x32_bf16 v[26:29], v[168:171], v[192:195], v[26:29]
	v_mfma_f32_16x16x32_bf16 v[14:17], v[138:141], v[200:203], v[14:17]
	v_mfma_f32_16x16x32_bf16 v[10:13], v[168:171], v[200:203], v[10:13]
	v_mfma_f32_16x16x32_bf16 v[62:65], v[164:167], v[180:183], v[62:65]
	v_mfma_f32_16x16x32_bf16 v[58:61], v[172:175], v[180:183], v[58:61]
	v_mfma_f32_16x16x32_bf16 v[46:49], v[164:167], v[188:191], v[46:49]
	v_mfma_f32_16x16x32_bf16 v[42:45], v[172:175], v[188:191], v[42:45]
	v_mfma_f32_16x16x32_bf16 v[30:33], v[164:167], v[196:199], v[30:33]
	v_mfma_f32_16x16x32_bf16 v[26:29], v[172:175], v[196:199], v[26:29]
	v_mfma_f32_16x16x32_bf16 v[14:17], v[164:167], v[204:207], v[14:17]
	v_mfma_f32_16x16x32_bf16 v[10:13], v[172:175], v[204:207], v[10:13]
	s_setprio 0
	s_barrier
	s_add_u32 s24, s24, 0x100080
	s_addc_u32 s25, s25, 0
	s_mov_b32 m0, s45
	v_lshl_add_u64 v[138:139], s[24:25], 0, v[132:133]
	global_load_lds_dwordx4 v[138:139], off
	v_lshl_add_u64 v[138:139], s[24:25], 0, v[130:131]
	s_mov_b32 m0, s46
	s_nop 0
	global_load_lds_dwordx4 v[138:139], off
	s_waitcnt vmcnt(6)
	s_barrier
	s_setprio 1
	v_mfma_f32_16x16x32_bf16 v[54:57], v[208:211], v[176:179], v[54:57]
	v_mfma_f32_16x16x32_bf16 v[50:53], v[216:219], v[176:179], v[50:53]
	v_mfma_f32_16x16x32_bf16 v[38:41], v[208:211], v[184:187], v[38:41]
	v_mfma_f32_16x16x32_bf16 v[34:37], v[216:219], v[184:187], v[34:37]
	v_mfma_f32_16x16x32_bf16 v[22:25], v[208:211], v[192:195], v[22:25]
	v_mfma_f32_16x16x32_bf16 v[18:21], v[216:219], v[192:195], v[18:21]
	v_mfma_f32_16x16x32_bf16 v[6:9], v[208:211], v[200:203], v[6:9]
	v_mfma_f32_16x16x32_bf16 v[2:5], v[216:219], v[200:203], v[2:5]
	v_mfma_f32_16x16x32_bf16 v[54:57], v[212:215], v[180:183], v[54:57]
	v_mfma_f32_16x16x32_bf16 v[50:53], v[220:223], v[180:183], v[50:53]
	v_mfma_f32_16x16x32_bf16 v[38:41], v[212:215], v[188:191], v[38:41]
	v_mfma_f32_16x16x32_bf16 v[34:37], v[220:223], v[188:191], v[34:37]
	v_mfma_f32_16x16x32_bf16 v[22:25], v[212:215], v[196:199], v[22:25]
	v_mfma_f32_16x16x32_bf16 v[18:21], v[220:223], v[196:199], v[18:21]
	v_mfma_f32_16x16x32_bf16 v[6:9], v[212:215], v[204:207], v[6:9]
	v_mfma_f32_16x16x32_bf16 v[2:5], v[220:223], v[204:207], v[2:5]
	s_setprio 0
	s_add_i32 s54, s54, 2
	s_add_u32 s22, s22, 0x100
	s_addc_u32 s23, s23, 0
	s_add_u32 s52, s52, 0x100
	s_addc_u32 s53, s53, 0
	s_cmp_gt_u32 s54, 61
	s_barrier
	s_cbranch_scc0 .LBB0_828
	v_lshl_or_b32 v138, s18, 8, v146
	v_and_b32_e32 v140, -9, v144
	v_bfe_u32 v214, v144, 3, 1
	v_lshl_add_u32 v140, s20, 8, v140
	v_ashrrev_i32_e32 v139, 31, v138
	v_ashrrev_i32_e32 v141, 31, v140
	v_lshlrev_b64 v[138:139], 2, v[138:139]
	v_lshlrev_b64 v[140:141], 12, v[140:141]
	v_lshlrev_b32_e32 v214, 6, v214
	v_mov_b32_e32 v215, 0
	v_lshl_add_u64 v[138:139], v[138:139], 0, v[214:215]
	v_lshl_add_u64 v[140:141], s[86:87], 0, v[140:141]
	v_lshl_add_u64 v[138:139], v[140:141], 0, v[138:139]
	s_mov_b64 s[62:63], 0x8000
	v_lshl_add_u64 v[140:141], v[138:139], 0, s[62:63]
	v_mov_b64_e32 v[212:213], v[138:139]
	v_mov_b64_e32 v[232:233], v[140:141]
	s_mov_b32 s60, 0xff00ff00
	s_mov_b32 s61, 0xff00ff00
	s_mov_b32 s18, s8
	s_mov_b32 s20, s10
	s_mov_b64 s[24:25], s[16:17]
	s_mov_b64 s[22:23], s[14:15]
	global_load_dwordx4 v[164:167], v[138:139], off
	global_load_dwordx4 v[168:171], v[138:139], off offset:512
	global_load_dwordx4 v[172:175], v[140:141], off
	global_load_dwordx4 v[176:179], v[140:141], off offset:512
	s_mov_b64 s[62:63], 0x10000
	v_lshl_add_u64 v[138:139], v[138:139], 0, s[62:63]
	v_lshl_add_u64 v[140:141], v[140:141], 0, s[62:63]
	global_load_dwordx4 v[180:183], v[138:139], off
	global_load_dwordx4 v[184:187], v[138:139], off offset:512
	global_load_dwordx4 v[188:191], v[140:141], off
	global_load_dwordx4 v[192:195], v[140:141], off offset:512
	v_mov_b32_dpp v228, v122 row_ror:8 row_mask:0xf bank_mask:0xf
	v_mov_b32_dpp v229, v123 row_ror:8 row_mask:0xf bank_mask:0xf
	v_mov_b32_dpp v230, v124 row_ror:8 row_mask:0xf bank_mask:0xf
	v_mov_b32_dpp v231, v125 row_ror:8 row_mask:0xf bank_mask:0xf
	v_mov_b32_dpp v234, v126 row_ror:8 row_mask:0xf bank_mask:0xf
	v_mov_b32_dpp v235, v127 row_ror:8 row_mask:0xf bank_mask:0xf
	v_mov_b32_dpp v236, v128 row_ror:8 row_mask:0xf bank_mask:0xf
	v_mov_b32_dpp v237, v129 row_ror:8 row_mask:0xf bank_mask:0xf
	v_cndmask_b32_e64 v126, v126, v228, s[60:61]
	v_cndmask_b32_e64 v127, v127, v229, s[60:61]
	v_cndmask_b32_e64 v128, v128, v230, s[60:61]
	v_cndmask_b32_e64 v129, v129, v231, s[60:61]
	v_cndmask_b32_e64 v122, v234, v122, s[60:61]
	v_cndmask_b32_e64 v123, v235, v123, s[60:61]
	v_cndmask_b32_e64 v124, v236, v124, s[60:61]
	v_cndmask_b32_e64 v125, v237, v125, s[60:61]
	v_mov_b32_dpp v228, v110 row_ror:8 row_mask:0xf bank_mask:0xf
	v_mov_b32_dpp v229, v111 row_ror:8 row_mask:0xf bank_mask:0xf
	v_mov_b32_dpp v230, v112 row_ror:8 row_mask:0xf bank_mask:0xf
	v_mov_b32_dpp v231, v113 row_ror:8 row_mask:0xf bank_mask:0xf
	v_mov_b32_dpp v234, v118 row_ror:8 row_mask:0xf bank_mask:0xf
	v_mov_b32_dpp v235, v119 row_ror:8 row_mask:0xf bank_mask:0xf
	v_mov_b32_dpp v236, v120 row_ror:8 row_mask:0xf bank_mask:0xf
	v_mov_b32_dpp v237, v121 row_ror:8 row_mask:0xf bank_mask:0xf
	v_cndmask_b32_e64 v118, v118, v228, s[60:61]
	v_cndmask_b32_e64 v119, v119, v229, s[60:61]
	v_cndmask_b32_e64 v120, v120, v230, s[60:61]
	v_cndmask_b32_e64 v121, v121, v231, s[60:61]
	v_cndmask_b32_e64 v110, v234, v110, s[60:61]
	v_cndmask_b32_e64 v111, v235, v111, s[60:61]
	v_cndmask_b32_e64 v112, v236, v112, s[60:61]
	v_cndmask_b32_e64 v113, v237, v113, s[60:61]
	s_mov_b64 s[62:63], 0x10000
	v_lshl_add_u64 v[138:139], v[138:139], 0, s[62:63]
	v_lshl_add_u64 v[140:141], v[140:141], 0, s[62:63]
	global_load_dwordx4 v[196:199], v[138:139], off
	global_load_dwordx4 v[200:203], v[138:139], off offset:512
	global_load_dwordx4 v[204:207], v[140:141], off
	global_load_dwordx4 v[208:211], v[140:141], off offset:512
	s_waitcnt vmcnt(8)
;   __device__ __forceinline__ void operator()(const acc8_t& acc, const pg8::Unit& u, int wr, int wc, int fr, int fq) const {
;     ...
;     for (int ai = 0; ai < 2; ai++)
; #pragma unroll
;       for (int m = 0; m < 4; m++) {
;         const size_t token = EPI_TOKEN(u, ai, m);
; #pragma unroll
;         for (int bj = 0; bj < 2; bj++)
; #pragma unroll
;           for (int n = 0; n < 2; n++) {
;             float* yp = out + O_Y + token * 1024 + EPI_COL(u, bj, n);
;             float4 y = *(const float4*)yp;
;             y.x += acc[ai][bj][m][n][0]; y.y += acc[ai][bj][m][n][1]; y.z += acc[ai][bj][m][n][2]; y.w += acc[ai][bj][m][n][3];
;             *(float4*)yp = y;
;           }
	v_pk_add_f32 v[164:165], v[126:127], v[164:165]
	v_pk_add_f32 v[166:167], v[128:129], v[166:167]
	v_pk_add_f32 v[172:173], v[122:123], v[172:173]
	v_pk_add_f32 v[174:175], v[124:125], v[174:175]
	v_pk_add_f32 v[168:169], v[118:119], v[168:169]
	v_pk_add_f32 v[170:171], v[120:121], v[170:171]
	v_pk_add_f32 v[176:177], v[110:111], v[176:177]
	v_pk_add_f32 v[178:179], v[112:113], v[178:179]
	global_store_dwordx4 v[212:213], v[164:167], off
	global_store_dwordx4 v[212:213], v[168:171], off offset:512
	global_store_dwordx4 v[232:233], v[172:175], off
	global_store_dwordx4 v[232:233], v[176:179], off offset:512
	s_mov_b64 s[62:63], 0x10000
	v_lshl_add_u64 v[212:213], v[212:213], 0, s[62:63]
	v_lshl_add_u64 v[232:233], v[232:233], 0, s[62:63]
	v_mov_b32_dpp v228, v106 row_ror:8 row_mask:0xf bank_mask:0xf
	v_mov_b32_dpp v229, v107 row_ror:8 row_mask:0xf bank_mask:0xf
	v_mov_b32_dpp v230, v108 row_ror:8 row_mask:0xf bank_mask:0xf
	v_mov_b32_dpp v231, v109 row_ror:8 row_mask:0xf bank_mask:0xf
	v_mov_b32_dpp v234, v114 row_ror:8 row_mask:0xf bank_mask:0xf
	v_mov_b32_dpp v235, v115 row_ror:8 row_mask:0xf bank_mask:0xf
	v_mov_b32_dpp v236, v116 row_ror:8 row_mask:0xf bank_mask:0xf
	v_mov_b32_dpp v237, v117 row_ror:8 row_mask:0xf bank_mask:0xf
	v_cndmask_b32_e64 v114, v114, v228, s[60:61]
	v_cndmask_b32_e64 v115, v115, v229, s[60:61]
	v_cndmask_b32_e64 v116, v116, v230, s[60:61]
	v_cndmask_b32_e64 v117, v117, v231, s[60:61]
	v_cndmask_b32_e64 v106, v234, v106, s[60:61]
	v_cndmask_b32_e64 v107, v235, v107, s[60:61]
	v_cndmask_b32_e64 v108, v236, v108, s[60:61]
	v_cndmask_b32_e64 v109, v237, v109, s[60:61]
	v_mov_b32_dpp v228, v98 row_ror:8 row_mask:0xf bank_mask:0xf
	v_mov_b32_dpp v229, v99 row_ror:8 row_mask:0xf bank_mask:0xf
	v_mov_b32_dpp v230, v100 row_ror:8 row_mask:0xf bank_mask:0xf
	v_mov_b32_dpp v231, v101 row_ror:8 row_mask:0xf bank_mask:0xf
	v_mov_b32_dpp v234, v102 row_ror:8 row_mask:0xf bank_mask:0xf
	v_mov_b32_dpp v235, v103 row_ror:8 row_mask:0xf bank_mask:0xf
	v_mov_b32_dpp v236, v104 row_ror:8 row_mask:0xf bank_mask:0xf
	v_mov_b32_dpp v237, v105 row_ror:8 row_mask:0xf bank_mask:0xf
	v_cndmask_b32_e64 v102, v102, v228, s[60:61]
	v_cndmask_b32_e64 v103, v103, v229, s[60:61]
	v_cndmask_b32_e64 v104, v104, v230, s[60:61]
	v_cndmask_b32_e64 v105, v105, v231, s[60:61]
	v_cndmask_b32_e64 v98, v234, v98, s[60:61]
	v_cndmask_b32_e64 v99, v235, v99, s[60:61]
	v_cndmask_b32_e64 v100, v236, v100, s[60:61]
	v_cndmask_b32_e64 v101, v237, v101, s[60:61]
	s_mov_b64 s[62:63], 0x10000
	v_lshl_add_u64 v[138:139], v[138:139], 0, s[62:63]
	v_lshl_add_u64 v[140:141], v[140:141], 0, s[62:63]
	global_load_dwordx4 v[164:167], v[138:139], off
	global_load_dwordx4 v[168:171], v[138:139], off offset:512
	global_load_dwordx4 v[172:175], v[140:141], off
	global_load_dwordx4 v[176:179], v[140:141], off offset:512
	s_waitcnt vmcnt(12)
	v_pk_add_f32 v[180:181], v[114:115], v[180:181]
	v_pk_add_f32 v[182:183], v[116:117], v[182:183]
	v_pk_add_f32 v[188:189], v[106:107], v[188:189]
	v_pk_add_f32 v[190:191], v[108:109], v[190:191]
	v_pk_add_f32 v[184:185], v[102:103], v[184:185]
	v_pk_add_f32 v[186:187], v[104:105], v[186:187]
	v_pk_add_f32 v[192:193], v[98:99], v[192:193]
	v_pk_add_f32 v[194:195], v[100:101], v[194:195]
	global_store_dwordx4 v[212:213], v[180:183], off
	global_store_dwordx4 v[212:213], v[184:187], off offset:512
	global_store_dwordx4 v[232:233], v[188:191], off
	global_store_dwordx4 v[232:233], v[192:195], off offset:512
	s_mov_b64 s[62:63], 0x10000
	v_lshl_add_u64 v[212:213], v[212:213], 0, s[62:63]
	v_lshl_add_u64 v[232:233], v[232:233], 0, s[62:63]
	v_mov_b32_dpp v228, v90 row_ror:8 row_mask:0xf bank_mask:0xf
	v_mov_b32_dpp v229, v91 row_ror:8 row_mask:0xf bank_mask:0xf
	v_mov_b32_dpp v230, v92 row_ror:8 row_mask:0xf bank_mask:0xf
	v_mov_b32_dpp v231, v93 row_ror:8 row_mask:0xf bank_mask:0xf
	v_mov_b32_dpp v234, v94 row_ror:8 row_mask:0xf bank_mask:0xf
	v_mov_b32_dpp v235, v95 row_ror:8 row_mask:0xf bank_mask:0xf
	v_mov_b32_dpp v236, v96 row_ror:8 row_mask:0xf bank_mask:0xf
	v_mov_b32_dpp v237, v97 row_ror:8 row_mask:0xf bank_mask:0xf
	v_cndmask_b32_e64 v94, v94, v228, s[60:61]
	v_cndmask_b32_e64 v95, v95, v229, s[60:61]
	v_cndmask_b32_e64 v96, v96, v230, s[60:61]
	v_cndmask_b32_e64 v97, v97, v231, s[60:61]
	v_cndmask_b32_e64 v90, v234, v90, s[60:61]
	v_cndmask_b32_e64 v91, v235, v91, s[60:61]
	v_cndmask_b32_e64 v92, v236, v92, s[60:61]
	v_cndmask_b32_e64 v93, v237, v93, s[60:61]
	v_mov_b32_dpp v228, v82 row_ror:8 row_mask:0xf bank_mask:0xf
	v_mov_b32_dpp v229, v83 row_ror:8 row_mask:0xf bank_mask:0xf
	v_mov_b32_dpp v230, v84 row_ror:8 row_mask:0xf bank_mask:0xf
	v_mov_b32_dpp v231, v85 row_ror:8 row_mask:0xf bank_mask:0xf
	v_mov_b32_dpp v234, v86 row_ror:8 row_mask:0xf bank_mask:0xf
	v_mov_b32_dpp v235, v87 row_ror:8 row_mask:0xf bank_mask:0xf
	v_mov_b32_dpp v236, v88 row_ror:8 row_mask:0xf bank_mask:0xf
	v_mov_b32_dpp v237, v89 row_ror:8 row_mask:0xf bank_mask:0xf
	v_cndmask_b32_e64 v86, v86, v228, s[60:61]
	v_cndmask_b32_e64 v87, v87, v229, s[60:61]
	v_cndmask_b32_e64 v88, v88, v230, s[60:61]
	v_cndmask_b32_e64 v89, v89, v231, s[60:61]
	v_cndmask_b32_e64 v82, v234, v82, s[60:61]
	v_cndmask_b32_e64 v83, v235, v83, s[60:61]
	v_cndmask_b32_e64 v84, v236, v84, s[60:61]
	v_cndmask_b32_e64 v85, v237, v85, s[60:61]
	s_mov_b64 s[62:63], 0x50000
	v_lshl_add_u64 v[138:139], v[138:139], 0, s[62:63]
	v_lshl_add_u64 v[140:141], v[140:141], 0, s[62:63]
	global_load_dwordx4 v[180:183], v[138:139], off
	global_load_dwordx4 v[184:187], v[138:139], off offset:512
	global_load_dwordx4 v[188:191], v[140:141], off
	global_load_dwordx4 v[192:195], v[140:141], off offset:512
	s_waitcnt vmcnt(16)
;   __device__ __forceinline__ void operator()(const acc8_t& acc, const pg8::Unit& u, int wr, int wc, int fr, int fq) const {
;     ...
;     for (int ai = 0; ai < 2; ai++)
; #pragma unroll
;       for (int m = 0; m < 4; m++) {
;         const size_t token = EPI_TOKEN(u, ai, m);
; #pragma unroll
;         for (int bj = 0; bj < 2; bj++)
; #pragma unroll
;           for (int n = 0; n < 2; n++) {
;             float* yp = out + O_Y + token * 1024 + EPI_COL(u, bj, n);
;             float4 y = *(const float4*)yp;
;             y.x += acc[ai][bj][m][n][0]; y.y += acc[ai][bj][m][n][1]; y.z += acc[ai][bj][m][n][2]; y.w += acc[ai][bj][m][n][3];
;             *(float4*)yp = y;
;           }
	v_pk_add_f32 v[196:197], v[94:95], v[196:197]
	v_pk_add_f32 v[198:199], v[96:97], v[198:199]
	v_pk_add_f32 v[204:205], v[90:91], v[204:205]
	v_pk_add_f32 v[206:207], v[92:93], v[206:207]
	v_pk_add_f32 v[200:201], v[86:87], v[200:201]
	v_pk_add_f32 v[202:203], v[88:89], v[202:203]
	v_pk_add_f32 v[208:209], v[82:83], v[208:209]
	v_pk_add_f32 v[210:211], v[84:85], v[210:211]
	global_store_dwordx4 v[212:213], v[196:199], off
	global_store_dwordx4 v[212:213], v[200:203], off offset:512
	global_store_dwordx4 v[232:233], v[204:207], off
	global_store_dwordx4 v[232:233], v[208:211], off offset:512
	s_mov_b64 s[62:63], 0x10000
	v_lshl_add_u64 v[212:213], v[212:213], 0, s[62:63]
	v_lshl_add_u64 v[232:233], v[232:233], 0, s[62:63]
	v_mov_b32_dpp v228, v74 row_ror:8 row_mask:0xf bank_mask:0xf
	v_mov_b32_dpp v229, v75 row_ror:8 row_mask:0xf bank_mask:0xf
	v_mov_b32_dpp v230, v76 row_ror:8 row_mask:0xf bank_mask:0xf
	v_mov_b32_dpp v231, v77 row_ror:8 row_mask:0xf bank_mask:0xf
	v_mov_b32_dpp v234, v78 row_ror:8 row_mask:0xf bank_mask:0xf
	v_mov_b32_dpp v235, v79 row_ror:8 row_mask:0xf bank_mask:0xf
	v_mov_b32_dpp v236, v80 row_ror:8 row_mask:0xf bank_mask:0xf
	v_mov_b32_dpp v237, v81 row_ror:8 row_mask:0xf bank_mask:0xf
	v_cndmask_b32_e64 v78, v78, v228, s[60:61]
	v_cndmask_b32_e64 v79, v79, v229, s[60:61]
	v_cndmask_b32_e64 v80, v80, v230, s[60:61]
	v_cndmask_b32_e64 v81, v81, v231, s[60:61]
	v_cndmask_b32_e64 v74, v234, v74, s[60:61]
	v_cndmask_b32_e64 v75, v235, v75, s[60:61]
	v_cndmask_b32_e64 v76, v236, v76, s[60:61]
	v_cndmask_b32_e64 v77, v237, v77, s[60:61]
	v_mov_b32_dpp v228, v66 row_ror:8 row_mask:0xf bank_mask:0xf
	v_mov_b32_dpp v229, v67 row_ror:8 row_mask:0xf bank_mask:0xf
	v_mov_b32_dpp v230, v68 row_ror:8 row_mask:0xf bank_mask:0xf
	v_mov_b32_dpp v231, v69 row_ror:8 row_mask:0xf bank_mask:0xf
	v_mov_b32_dpp v234, v70 row_ror:8 row_mask:0xf bank_mask:0xf
	v_mov_b32_dpp v235, v71 row_ror:8 row_mask:0xf bank_mask:0xf
	v_mov_b32_dpp v236, v72 row_ror:8 row_mask:0xf bank_mask:0xf
	v_mov_b32_dpp v237, v73 row_ror:8 row_mask:0xf bank_mask:0xf
	v_cndmask_b32_e64 v70, v70, v228, s[60:61]
	v_cndmask_b32_e64 v71, v71, v229, s[60:61]
	v_cndmask_b32_e64 v72, v72, v230, s[60:61]
	v_cndmask_b32_e64 v73, v73, v231, s[60:61]
	v_cndmask_b32_e64 v66, v234, v66, s[60:61]
	v_cndmask_b32_e64 v67, v235, v67, s[60:61]
	v_cndmask_b32_e64 v68, v236, v68, s[60:61]
	v_cndmask_b32_e64 v69, v237, v69, s[60:61]
	s_mov_b64 s[62:63], 0x10000
	v_lshl_add_u64 v[138:139], v[138:139], 0, s[62:63]
	v_lshl_add_u64 v[140:141], v[140:141], 0, s[62:63]
	global_load_dwordx4 v[196:199], v[138:139], off
	global_load_dwordx4 v[200:203], v[138:139], off offset:512
	global_load_dwordx4 v[204:207], v[140:141], off
	global_load_dwordx4 v[208:211], v[140:141], off offset:512
	s_waitcnt vmcnt(16)
	v_pk_add_f32 v[164:165], v[78:79], v[164:165]
	v_pk_add_f32 v[166:167], v[80:81], v[166:167]
	v_pk_add_f32 v[172:173], v[74:75], v[172:173]
	v_pk_add_f32 v[174:175], v[76:77], v[174:175]
	v_pk_add_f32 v[168:169], v[70:71], v[168:169]
	v_pk_add_f32 v[170:171], v[72:73], v[170:171]
	v_pk_add_f32 v[176:177], v[66:67], v[176:177]
	v_pk_add_f32 v[178:179], v[68:69], v[178:179]
	global_store_dwordx4 v[212:213], v[164:167], off
	global_store_dwordx4 v[212:213], v[168:171], off offset:512
	global_store_dwordx4 v[232:233], v[172:175], off
	global_store_dwordx4 v[232:233], v[176:179], off offset:512
	s_mov_b64 s[62:63], 0x50000
	v_lshl_add_u64 v[212:213], v[212:213], 0, s[62:63]
	v_lshl_add_u64 v[232:233], v[232:233], 0, s[62:63]
	v_mov_b32_dpp v228, v58 row_ror:8 row_mask:0xf bank_mask:0xf
	v_mov_b32_dpp v229, v59 row_ror:8 row_mask:0xf bank_mask:0xf
	v_mov_b32_dpp v230, v60 row_ror:8 row_mask:0xf bank_mask:0xf
	v_mov_b32_dpp v231, v61 row_ror:8 row_mask:0xf bank_mask:0xf
	v_mov_b32_dpp v234, v62 row_ror:8 row_mask:0xf bank_mask:0xf
	v_mov_b32_dpp v235, v63 row_ror:8 row_mask:0xf bank_mask:0xf
	v_mov_b32_dpp v236, v64 row_ror:8 row_mask:0xf bank_mask:0xf
	v_mov_b32_dpp v237, v65 row_ror:8 row_mask:0xf bank_mask:0xf
	v_cndmask_b32_e64 v62, v62, v228, s[60:61]
	v_cndmask_b32_e64 v63, v63, v229, s[60:61]
	v_cndmask_b32_e64 v64, v64, v230, s[60:61]
	v_cndmask_b32_e64 v65, v65, v231, s[60:61]
	v_cndmask_b32_e64 v58, v234, v58, s[60:61]
	v_cndmask_b32_e64 v59, v235, v59, s[60:61]
	v_cndmask_b32_e64 v60, v236, v60, s[60:61]
	v_cndmask_b32_e64 v61, v237, v61, s[60:61]
	v_mov_b32_dpp v228, v50 row_ror:8 row_mask:0xf bank_mask:0xf
	v_mov_b32_dpp v229, v51 row_ror:8 row_mask:0xf bank_mask:0xf
	v_mov_b32_dpp v230, v52 row_ror:8 row_mask:0xf bank_mask:0xf
	v_mov_b32_dpp v231, v53 row_ror:8 row_mask:0xf bank_mask:0xf
	v_mov_b32_dpp v234, v54 row_ror:8 row_mask:0xf bank_mask:0xf
	v_mov_b32_dpp v235, v55 row_ror:8 row_mask:0xf bank_mask:0xf
	v_mov_b32_dpp v236, v56 row_ror:8 row_mask:0xf bank_mask:0xf
	v_mov_b32_dpp v237, v57 row_ror:8 row_mask:0xf bank_mask:0xf
	v_cndmask_b32_e64 v54, v54, v228, s[60:61]
	v_cndmask_b32_e64 v55, v55, v229, s[60:61]
	v_cndmask_b32_e64 v56, v56, v230, s[60:61]
	v_cndmask_b32_e64 v57, v57, v231, s[60:61]
	v_cndmask_b32_e64 v50, v234, v50, s[60:61]
	v_cndmask_b32_e64 v51, v235, v51, s[60:61]
	v_cndmask_b32_e64 v52, v236, v52, s[60:61]
	v_cndmask_b32_e64 v53, v237, v53, s[60:61]
	s_mov_b64 s[62:63], 0x10000
	v_lshl_add_u64 v[138:139], v[138:139], 0, s[62:63]
	v_lshl_add_u64 v[140:141], v[140:141], 0, s[62:63]
	global_load_dwordx4 v[164:167], v[138:139], off
	global_load_dwordx4 v[168:171], v[138:139], off offset:512
	global_load_dwordx4 v[172:175], v[140:141], off
	global_load_dwordx4 v[176:179], v[140:141], off offset:512
	s_waitcnt vmcnt(16)
;   __device__ __forceinline__ void operator()(const acc8_t& acc, const pg8::Unit& u, int wr, int wc, int fr, int fq) const {
;     ...
;     for (int ai = 0; ai < 2; ai++)
; #pragma unroll
;       for (int m = 0; m < 4; m++) {
;         const size_t token = EPI_TOKEN(u, ai, m);
; #pragma unroll
;         for (int bj = 0; bj < 2; bj++)
; #pragma unroll
;           for (int n = 0; n < 2; n++) {
;             float* yp = out + O_Y + token * 1024 + EPI_COL(u, bj, n);
;             float4 y = *(const float4*)yp;
;             y.x += acc[ai][bj][m][n][0]; y.y += acc[ai][bj][m][n][1]; y.z += acc[ai][bj][m][n][2]; y.w += acc[ai][bj][m][n][3];
;             *(float4*)yp = y;
;           }
	v_pk_add_f32 v[180:181], v[62:63], v[180:181]
	v_pk_add_f32 v[182:183], v[64:65], v[182:183]
	v_pk_add_f32 v[188:189], v[58:59], v[188:189]
	v_pk_add_f32 v[190:191], v[60:61], v[190:191]
	v_pk_add_f32 v[184:185], v[54:55], v[184:185]
	v_pk_add_f32 v[186:187], v[56:57], v[186:187]
	v_pk_add_f32 v[192:193], v[50:51], v[192:193]
	v_pk_add_f32 v[194:195], v[52:53], v[194:195]
	global_store_dwordx4 v[212:213], v[180:183], off
	global_store_dwordx4 v[212:213], v[184:187], off offset:512
	global_store_dwordx4 v[232:233], v[188:191], off
	global_store_dwordx4 v[232:233], v[192:195], off offset:512
	s_mov_b64 s[62:63], 0x10000
	v_lshl_add_u64 v[212:213], v[212:213], 0, s[62:63]
	v_lshl_add_u64 v[232:233], v[232:233], 0, s[62:63]
	v_mov_b32_dpp v228, v42 row_ror:8 row_mask:0xf bank_mask:0xf
	v_mov_b32_dpp v229, v43 row_ror:8 row_mask:0xf bank_mask:0xf
	v_mov_b32_dpp v230, v44 row_ror:8 row_mask:0xf bank_mask:0xf
	v_mov_b32_dpp v231, v45 row_ror:8 row_mask:0xf bank_mask:0xf
	v_mov_b32_dpp v234, v46 row_ror:8 row_mask:0xf bank_mask:0xf
	v_mov_b32_dpp v235, v47 row_ror:8 row_mask:0xf bank_mask:0xf
	v_mov_b32_dpp v236, v48 row_ror:8 row_mask:0xf bank_mask:0xf
	v_mov_b32_dpp v237, v49 row_ror:8 row_mask:0xf bank_mask:0xf
	v_cndmask_b32_e64 v46, v46, v228, s[60:61]
	v_cndmask_b32_e64 v47, v47, v229, s[60:61]
	v_cndmask_b32_e64 v48, v48, v230, s[60:61]
	v_cndmask_b32_e64 v49, v49, v231, s[60:61]
	v_cndmask_b32_e64 v42, v234, v42, s[60:61]
	v_cndmask_b32_e64 v43, v235, v43, s[60:61]
	v_cndmask_b32_e64 v44, v236, v44, s[60:61]
	v_cndmask_b32_e64 v45, v237, v45, s[60:61]
	v_mov_b32_dpp v228, v34 row_ror:8 row_mask:0xf bank_mask:0xf
	v_mov_b32_dpp v229, v35 row_ror:8 row_mask:0xf bank_mask:0xf
	v_mov_b32_dpp v230, v36 row_ror:8 row_mask:0xf bank_mask:0xf
	v_mov_b32_dpp v231, v37 row_ror:8 row_mask:0xf bank_mask:0xf
	v_mov_b32_dpp v234, v38 row_ror:8 row_mask:0xf bank_mask:0xf
	v_mov_b32_dpp v235, v39 row_ror:8 row_mask:0xf bank_mask:0xf
	v_mov_b32_dpp v236, v40 row_ror:8 row_mask:0xf bank_mask:0xf
	v_mov_b32_dpp v237, v41 row_ror:8 row_mask:0xf bank_mask:0xf
	v_cndmask_b32_e64 v38, v38, v228, s[60:61]
	v_cndmask_b32_e64 v39, v39, v229, s[60:61]
	v_cndmask_b32_e64 v40, v40, v230, s[60:61]
	v_cndmask_b32_e64 v41, v41, v231, s[60:61]
	v_cndmask_b32_e64 v34, v234, v34, s[60:61]
	v_cndmask_b32_e64 v35, v235, v35, s[60:61]
	v_cndmask_b32_e64 v36, v236, v36, s[60:61]
	v_cndmask_b32_e64 v37, v237, v37, s[60:61]
	s_mov_b64 s[62:63], 0x10000
	v_lshl_add_u64 v[138:139], v[138:139], 0, s[62:63]
	v_lshl_add_u64 v[140:141], v[140:141], 0, s[62:63]
	global_load_dwordx4 v[180:183], v[138:139], off
	global_load_dwordx4 v[184:187], v[138:139], off offset:512
	global_load_dwordx4 v[188:191], v[140:141], off
	global_load_dwordx4 v[192:195], v[140:141], off offset:512
	s_waitcnt vmcnt(16)
	v_pk_add_f32 v[196:197], v[46:47], v[196:197]
	v_pk_add_f32 v[198:199], v[48:49], v[198:199]
	v_pk_add_f32 v[204:205], v[42:43], v[204:205]
	v_pk_add_f32 v[206:207], v[44:45], v[206:207]
	v_pk_add_f32 v[200:201], v[38:39], v[200:201]
	v_pk_add_f32 v[202:203], v[40:41], v[202:203]
	v_pk_add_f32 v[208:209], v[34:35], v[208:209]
	v_pk_add_f32 v[210:211], v[36:37], v[210:211]
	global_store_dwordx4 v[212:213], v[196:199], off
	global_store_dwordx4 v[212:213], v[200:203], off offset:512
	global_store_dwordx4 v[232:233], v[204:207], off
	global_store_dwordx4 v[232:233], v[208:211], off offset:512
	s_mov_b64 s[62:63], 0x10000
	v_lshl_add_u64 v[212:213], v[212:213], 0, s[62:63]
	v_lshl_add_u64 v[232:233], v[232:233], 0, s[62:63]
	v_mov_b32_dpp v228, v26 row_ror:8 row_mask:0xf bank_mask:0xf
	v_mov_b32_dpp v229, v27 row_ror:8 row_mask:0xf bank_mask:0xf
	v_mov_b32_dpp v230, v28 row_ror:8 row_mask:0xf bank_mask:0xf
	v_mov_b32_dpp v231, v29 row_ror:8 row_mask:0xf bank_mask:0xf
	v_mov_b32_dpp v234, v30 row_ror:8 row_mask:0xf bank_mask:0xf
	v_mov_b32_dpp v235, v31 row_ror:8 row_mask:0xf bank_mask:0xf
	v_mov_b32_dpp v236, v32 row_ror:8 row_mask:0xf bank_mask:0xf
	v_mov_b32_dpp v237, v33 row_ror:8 row_mask:0xf bank_mask:0xf
	v_cndmask_b32_e64 v30, v30, v228, s[60:61]
	v_cndmask_b32_e64 v31, v31, v229, s[60:61]
	v_cndmask_b32_e64 v32, v32, v230, s[60:61]
	v_cndmask_b32_e64 v33, v33, v231, s[60:61]
	v_cndmask_b32_e64 v26, v234, v26, s[60:61]
	v_cndmask_b32_e64 v27, v235, v27, s[60:61]
	v_cndmask_b32_e64 v28, v236, v28, s[60:61]
	v_cndmask_b32_e64 v29, v237, v29, s[60:61]
	v_mov_b32_dpp v228, v18 row_ror:8 row_mask:0xf bank_mask:0xf
	v_mov_b32_dpp v229, v19 row_ror:8 row_mask:0xf bank_mask:0xf
	v_mov_b32_dpp v230, v20 row_ror:8 row_mask:0xf bank_mask:0xf
	v_mov_b32_dpp v231, v21 row_ror:8 row_mask:0xf bank_mask:0xf
	v_mov_b32_dpp v234, v22 row_ror:8 row_mask:0xf bank_mask:0xf
	v_mov_b32_dpp v235, v23 row_ror:8 row_mask:0xf bank_mask:0xf
	v_mov_b32_dpp v236, v24 row_ror:8 row_mask:0xf bank_mask:0xf
	v_mov_b32_dpp v237, v25 row_ror:8 row_mask:0xf bank_mask:0xf
	v_cndmask_b32_e64 v22, v22, v228, s[60:61]
	v_cndmask_b32_e64 v23, v23, v229, s[60:61]
	v_cndmask_b32_e64 v24, v24, v230, s[60:61]
	v_cndmask_b32_e64 v25, v25, v231, s[60:61]
	v_cndmask_b32_e64 v18, v234, v18, s[60:61]
	v_cndmask_b32_e64 v19, v235, v19, s[60:61]
	v_cndmask_b32_e64 v20, v236, v20, s[60:61]
	v_cndmask_b32_e64 v21, v237, v21, s[60:61]
	s_waitcnt vmcnt(12)
; #define PG8_WAIT_V(n) asm volatile("s_waitcnt vmcnt(" #n ")" ::: "memory")
; #define PG8_BAR __builtin_amdgcn_s_barrier()
; template <class Epi, class Sched>
; __device__ __forceinline__ void gemm_phase(PG8_LAS unsigned char* lds, const Gemm g, const Sched& S, const Epi& E) {
;     ...
;     PG8_WAIT_V(0);
;     if (wr == 0) PG8_BAR;
;     PG8_BAR;
;   __device__ __forceinline__ void operator()(const acc8_t& acc, const pg8::Unit& u, int wr, int wc, int fr, int fq) const {
;     ...
;     for (int ai = 0; ai < 2; ai++)
; #pragma unroll
;       for (int m = 0; m < 4; m++) {
;         const size_t token = EPI_TOKEN(u, ai, m);
; #pragma unroll
;         for (int bj = 0; bj < 2; bj++)
; #pragma unroll
;           for (int n = 0; n < 2; n++) {
;             float* yp = out + O_Y + token * 1024 + EPI_COL(u, bj, n);
;             float4 y = *(const float4*)yp;
;             y.x += acc[ai][bj][m][n][0]; y.y += acc[ai][bj][m][n][1]; y.z += acc[ai][bj][m][n][2]; y.w += acc[ai][bj][m][n][3];
;             *(float4*)yp = y;
;           }
	v_pk_add_f32 v[164:165], v[30:31], v[164:165]
	v_pk_add_f32 v[166:167], v[32:33], v[166:167]
	v_pk_add_f32 v[172:173], v[26:27], v[172:173]
	v_pk_add_f32 v[174:175], v[28:29], v[174:175]
	v_pk_add_f32 v[168:169], v[22:23], v[168:169]
	v_pk_add_f32 v[170:171], v[24:25], v[170:171]
	v_pk_add_f32 v[176:177], v[18:19], v[176:177]
	v_pk_add_f32 v[178:179], v[20:21], v[178:179]
	global_store_dwordx4 v[212:213], v[164:167], off
	global_store_dwordx4 v[212:213], v[168:171], off offset:512
	global_store_dwordx4 v[232:233], v[172:175], off
	global_store_dwordx4 v[232:233], v[176:179], off offset:512
	s_mov_b64 s[62:63], 0x10000
	v_lshl_add_u64 v[212:213], v[212:213], 0, s[62:63]
	v_lshl_add_u64 v[232:233], v[232:233], 0, s[62:63]
	v_mov_b32_dpp v228, v10 row_ror:8 row_mask:0xf bank_mask:0xf
	v_mov_b32_dpp v229, v11 row_ror:8 row_mask:0xf bank_mask:0xf
	v_mov_b32_dpp v230, v12 row_ror:8 row_mask:0xf bank_mask:0xf
	v_mov_b32_dpp v231, v13 row_ror:8 row_mask:0xf bank_mask:0xf
	v_mov_b32_dpp v234, v14 row_ror:8 row_mask:0xf bank_mask:0xf
	v_mov_b32_dpp v235, v15 row_ror:8 row_mask:0xf bank_mask:0xf
	v_mov_b32_dpp v236, v16 row_ror:8 row_mask:0xf bank_mask:0xf
	v_mov_b32_dpp v237, v17 row_ror:8 row_mask:0xf bank_mask:0xf
	v_cndmask_b32_e64 v14, v14, v228, s[60:61]
	v_cndmask_b32_e64 v15, v15, v229, s[60:61]
	v_cndmask_b32_e64 v16, v16, v230, s[60:61]
	v_cndmask_b32_e64 v17, v17, v231, s[60:61]
	v_cndmask_b32_e64 v10, v234, v10, s[60:61]
	v_cndmask_b32_e64 v11, v235, v11, s[60:61]
	v_cndmask_b32_e64 v12, v236, v12, s[60:61]
	v_cndmask_b32_e64 v13, v237, v13, s[60:61]
	v_mov_b32_dpp v228, v2 row_ror:8 row_mask:0xf bank_mask:0xf
	v_mov_b32_dpp v229, v3 row_ror:8 row_mask:0xf bank_mask:0xf
	v_mov_b32_dpp v230, v4 row_ror:8 row_mask:0xf bank_mask:0xf
	v_mov_b32_dpp v231, v5 row_ror:8 row_mask:0xf bank_mask:0xf
	v_mov_b32_dpp v234, v6 row_ror:8 row_mask:0xf bank_mask:0xf
	v_mov_b32_dpp v235, v7 row_ror:8 row_mask:0xf bank_mask:0xf
	v_mov_b32_dpp v236, v8 row_ror:8 row_mask:0xf bank_mask:0xf
	v_mov_b32_dpp v237, v9 row_ror:8 row_mask:0xf bank_mask:0xf
	v_cndmask_b32_e64 v6, v6, v228, s[60:61]
	v_cndmask_b32_e64 v7, v7, v229, s[60:61]
	v_cndmask_b32_e64 v8, v8, v230, s[60:61]
	v_cndmask_b32_e64 v9, v9, v231, s[60:61]
	v_cndmask_b32_e64 v2, v234, v2, s[60:61]
	v_cndmask_b32_e64 v3, v235, v3, s[60:61]
	v_cndmask_b32_e64 v4, v236, v4, s[60:61]
	v_cndmask_b32_e64 v5, v237, v5, s[60:61]
	s_waitcnt vmcnt(8)
	v_pk_add_f32 v[180:181], v[14:15], v[180:181]
	v_pk_add_f32 v[182:183], v[16:17], v[182:183]
	v_pk_add_f32 v[188:189], v[10:11], v[188:189]
	v_pk_add_f32 v[190:191], v[12:13], v[190:191]
	v_pk_add_f32 v[184:185], v[6:7], v[184:185]
	v_pk_add_f32 v[186:187], v[8:9], v[186:187]
	v_pk_add_f32 v[192:193], v[2:3], v[192:193]
	v_pk_add_f32 v[194:195], v[4:5], v[194:195]
	global_store_dwordx4 v[212:213], v[180:183], off
	global_store_dwordx4 v[212:213], v[184:187], off offset:512
	global_store_dwordx4 v[232:233], v[188:191], off
	global_store_dwordx4 v[232:233], v[192:195], off offset:512
	s_and_b64 vcc, exec, s[12:13]
	s_cbranch_vccz .LBB0_825
	s_waitcnt vmcnt(0)
	s_cmpk_gt_u32 s34, 0xff
	s_cbranch_scc1 .LBB0_832
	s_barrier
